# P1 woven first iteration: third counted wait relaxed to vmcnt(12) so it does not wait for the deferred epilogue stores
# speedup vs baseline: 1.0010x; 1.0006x over previous
; #define PG8_STAGE(bufoff, gbase, voff) do { _Pragma("unroll") for (int _i = 0; _i < 2; ++_i) \
;         __builtin_amdgcn_global_load_lds((const unsigned*)((const char*)(gbase) + (voff)[_i]), (PG8_LAS unsigned*)(lds + (bufoff) + ldsw + _i * 8192), 16, 0, 0); } while (0)
; #define PG8_LDA(dst, b, h) do { _Pragma("unroll") for (int m = 0; m < 4; ++m) _Pragma("unroll") for (int k = 0; k < 2; ++k) dst[m][k] = *(const PG8_LAS bf16x8*)(lds + PG8_SA(b, h) + aoff + m * 2048 + k * 1024); } while (0)
; #define PG8_SCHED __builtin_amdgcn_sched_barrier(0)
; __device__ __forceinline__ unsigned pk2(float lo, float hi) { return pg8::cvt_pk_bf16(lo, hi); }
; template <class Epi, class Sched, bool ALIGN_EPI = false, bool SP2 = false>
; __device__ __forceinline__ void gemm_phase(PG8_LAS unsigned char* lds, const Gemm g, const Sched& S, const Epi& E) {
;     ...
;         const bool has_next = S.next(ui + 1, nxt);
;         const char* nA = has_next ? (const char*)g.A + (size_t)nxt.pm * tstep : cA; const char* nB = has_next ? (const char*)g.Bt + (size_t)nxt.pn * tstep : cB;
;         for (int t = 0; t < nt; t += 2) {
;             const bool last = (t == nt - 2);
;             const char* a1 = cA + (size_t)(t + 1) * kstep;
;             const char* a2 = last ? nA : cA + (size_t)(t + 2) * kstep; const char* b2 = last ? nB : cB + (size_t)(t + 2) * kstep;
;             const char* a3 = a2 + kstep; const char* b3 = b2 + kstep;
;             if (last && has_next) S.a_ready(nxt);
;             if constexpr (SP2) {
;             PG8_LDB(B0, 0, 0); PG8_LDB(B1, 0, 1); PG8_SCHED; PG8_LDA(At, 0, 0); PG8_STAGE(PG8_SA(1, 1), a1 + hstep, voffA);
;     __device__ __forceinline__ void operator()(const f32x4 (&acc)[2][2][4][2], const pg8::Unit& u, int wr, int wc, int fr, int fq) const {
;     ...
;                 const int row = row0 + ai * 128 + m * 16;
;                 const float rs = sumsq ? rsqrtf(sumsq[row] * (1.f / 1024.f) + EPS) : 1.f;
;                 float o[8];
; #pragma unroll
;                 for (int n = 0; n < 2; ++n)
; #pragma unroll
;                     for (int e = 0; e < 4; ++e) { const float g = acc[ai][0][m][n][e] * rs, up = acc[ai][1][m][n][e] * rs; o[4 * n + e] = silu_f(g) * up; }
;                 u32x4 w; w.x = pk2(o[0], o[1]); w.y = pk2(o[2], o[3]); w.z = pk2(o[4], o[5]); w.w = pk2(o[6], o[7]);
;                 *(u32x4*)(H + (size_t)row * DFF + col) = w;
.LBB0_191:
	s_ashr_i32 s15, s14, 31
	s_lshl_b64 s[16:17], s[14:15], 19
	v_readlane_b32 s18, v235, 31
	v_readlane_b32 s19, v235, 32
	s_add_u32 s16, s18, s16
	s_addc_u32 s17, s19, s17
	s_and_b64 s[18:19], s[0:1], exec
	s_cselect_b32 s15, s17, s23
	s_cselect_b32 s50, s16, s22
	s_ashr_i32 s9, s8, 31
	s_lshl_b64 s[18:19], s[8:9], 19
	s_add_u32 s18, s33, s18
	s_addc_u32 s19, s34, s19
	s_and_b64 s[30:31], s[0:1], exec
	s_cselect_b32 s9, s19, s25
	s_cselect_b32 s51, s18, s24
	s_add_u32 s22, s22, 0x40080
	s_addc_u32 s23, s23, 0
	s_add_u32 s52, s24, 0x100
	s_addc_u32 s53, s25, 0
	s_mov_b32 s54, -2
	s_cmp_eq_u32 s98, 0
	s_cbranch_scc1 .Lp1_plain
	ds_read_b128 v[150:153], v147
	ds_read_b128 v[154:157], v147 offset:1024
	ds_read_b128 v[158:161], v147 offset:2048
	ds_read_b128 v[162:165], v147 offset:3072
	ds_read_b128 v[166:169], v148
	ds_read_b128 v[170:173], v148 offset:1024
	ds_read_b128 v[174:177], v148 offset:2048
	ds_read_b128 v[178:181], v148 offset:3072
	s_add_u32 s24, s22, 0xfffc0080
	s_addc_u32 s25, s23, -1
	s_cmp_eq_u32 s54, 12
	s_cselect_b32 s31, s15, s25
	s_cselect_b32 s30, s50, s24
	s_cselect_b32 s25, s9, s53
	s_cselect_b32 s24, s51, s52
	v_lshl_add_u64 v[186:187], s[22:23], 0, v[136:137]
	s_add_i32 m0, s21, 0xc000
	ds_read_b128 v[182:185], v149
	ds_read_b128 v[192:195], v149 offset:1024
	ds_read_b128 v[196:199], v149 offset:2048
	ds_read_b128 v[200:203], v149 offset:3072
	ds_read_b128 v[204:207], v149 offset:4096
	ds_read_b128 v[208:211], v149 offset:5120
	ds_read_b128 v[212:215], v149 offset:6144
	ds_read_b128 v[216:219], v149 offset:7168
	global_load_lds_dwordx4 v[186:187], off
	v_lshl_add_u64 v[186:187], s[22:23], 0, v[138:139]
	s_add_i32 m0, s21, 0xe000
	s_nop 0
	global_load_lds_dwordx4 v[186:187], off
	s_nop 1
	v_add_f32_e32 v64, 1.0, v70
	v_rcp_f32_e32 v64, v64
	v_add_f32_e32 v65, 1.0, v71
	v_rcp_f32_e32 v65, v65
	v_add_u32_e32 v66, 0x80, v228
	v_mul_f32_e32 v60, v60, v64
	v_mul_f32_e32 v52, v60, v52
	v_mul_f32_e32 v60, v61, v65
	v_mul_f32_e32 v61, 0xbfb8aa3b, v62
	v_exp_f32_e32 v61, v61
	v_mul_f32_e32 v64, 0xbfb8aa3b, v63
	v_exp_f32_e32 v64, v64
	v_mul_f32_e32 v53, v60, v53
	v_add_f32_e32 v60, 1.0, v61
	v_rcp_f32_e32 v60, v60
	v_add_f32_e32 v61, 1.0, v64
	v_mul_f32_e32 v64, 0xbfb8aa3b, v56
	v_rcp_f32_e32 v61, v61
	v_exp_f32_e32 v64, v64
	v_mul_f32_e32 v60, v62, v60
	v_mul_f32_e32 v54, v60, v54
	v_mul_f32_e32 v60, v63, v61
	v_add_f32_e32 v61, 1.0, v64
	v_rcp_f32_e32 v61, v61
	v_mul_f32_e32 v62, 0xbfb8aa3b, v57
	v_exp_f32_e32 v62, v62
	v_mul_f32_e32 v55, v60, v55
	v_mul_f32_e32 v56, v56, v61
	v_mul_f32_e32 v56, v56, v48
	v_add_f32_e32 v48, 1.0, v62
	v_mul_f32_e32 v60, 0xbfb8aa3b, v58
	v_rcp_f32_e32 v48, v48
	v_exp_f32_e32 v60, v60
	v_mul_f32_e32 v61, 0xbfb8aa3b, v59
	v_exp_f32_e32 v61, v61
	v_mul_f32_e32 v48, v57, v48
	v_add_f32_e32 v57, 1.0, v60
	v_rcp_f32_e32 v57, v57
	v_add_f32_e32 v60, 1.0, v61
	v_rcp_f32_e32 v60, v60
	v_mul_f32_e32 v61, v48, v49
	v_mul_f32_e32 v48, v58, v57
	v_mul_f32_e32 v57, v48, v50
	v_mul_f32_e32 v48, v59, v60
	v_mul_f32_e32 v51, v48, v51
	v_cvt_pk_bf16_f32 v48, v52, v53
	v_cvt_pk_bf16_f32 v49, v54, v55
	v_mul_f32_e32 v54, 0xbfb8aa3b, v44
	v_exp_f32_e32 v54, v54
	v_mul_f32_e32 v55, 0xbfb8aa3b, v45
	v_exp_f32_e32 v55, v55
	v_mad_i64_i32 v[52:53], s[100:101], v66, s48, v[112:113]
	v_lshl_add_u64 v[52:53], v[52:53], 0, v[114:115]
	v_cvt_pk_bf16_f32 v50, v56, v61
	v_cvt_pk_bf16_f32 v51, v57, v51
	global_store_dwordx4 v[52:53], v[48:51], off
	s_nop 1
	v_add_f32_e32 v48, 1.0, v54
	v_rcp_f32_e32 v48, v48
	v_add_f32_e32 v49, 1.0, v55
	v_rcp_f32_e32 v49, v49
	v_add_u32_e32 v50, 0x90, v228
	v_mul_f32_e32 v44, v44, v48
	v_mul_f32_e32 v36, v44, v36
	v_mul_f32_e32 v44, v45, v49
	v_mul_f32_e32 v45, 0xbfb8aa3b, v46
	v_exp_f32_e32 v45, v45
	v_mul_f32_e32 v48, 0xbfb8aa3b, v47
	v_exp_f32_e32 v48, v48
	v_mul_f32_e32 v37, v44, v37
	v_add_f32_e32 v44, 1.0, v45
	v_rcp_f32_e32 v44, v44
	v_add_f32_e32 v45, 1.0, v48
	v_mul_f32_e32 v48, 0xbfb8aa3b, v40
	v_rcp_f32_e32 v45, v45
	v_exp_f32_e32 v48, v48
	v_mul_f32_e32 v44, v46, v44
	v_mul_f32_e32 v38, v44, v38
	v_mul_f32_e32 v44, v47, v45
	v_add_f32_e32 v45, 1.0, v48
	v_rcp_f32_e32 v45, v45
	v_mul_f32_e32 v46, 0xbfb8aa3b, v41
	v_exp_f32_e32 v46, v46
	v_mul_f32_e32 v39, v44, v39
	v_mul_f32_e32 v40, v40, v45
	v_mul_f32_e32 v40, v40, v32
	v_add_f32_e32 v32, 1.0, v46
	v_mul_f32_e32 v44, 0xbfb8aa3b, v42
	v_rcp_f32_e32 v32, v32
	v_exp_f32_e32 v44, v44
	v_mul_f32_e32 v45, 0xbfb8aa3b, v43
	v_exp_f32_e32 v45, v45
	v_mul_f32_e32 v32, v41, v32
	v_add_f32_e32 v41, 1.0, v44
	v_rcp_f32_e32 v41, v41
	v_add_f32_e32 v44, 1.0, v45
	v_rcp_f32_e32 v44, v44
	v_mul_f32_e32 v45, v32, v33
	v_mul_f32_e32 v32, v42, v41
	v_mul_f32_e32 v41, v32, v34
	v_mul_f32_e32 v32, v43, v44
	v_mul_f32_e32 v35, v32, v35
	v_cvt_pk_bf16_f32 v32, v36, v37
	v_cvt_pk_bf16_f32 v33, v38, v39
	v_mul_f32_e32 v38, 0xbfb8aa3b, v28
	v_exp_f32_e32 v38, v38
	v_mul_f32_e32 v39, 0xbfb8aa3b, v29
	v_exp_f32_e32 v39, v39
	v_mad_i64_i32 v[36:37], s[100:101], v50, s48, v[112:113]
	v_lshl_add_u64 v[36:37], v[36:37], 0, v[114:115]
	v_cvt_pk_bf16_f32 v34, v40, v45
	v_cvt_pk_bf16_f32 v35, v41, v35
	global_store_dwordx4 v[36:37], v[32:35], off
	s_nop 1
	v_add_f32_e32 v32, 1.0, v38
	v_rcp_f32_e32 v32, v32
	v_add_f32_e32 v33, 1.0, v39
	v_rcp_f32_e32 v33, v33
	v_add_u32_e32 v34, 0xa0, v228
	v_mul_f32_e32 v28, v28, v32
	v_mul_f32_e32 v20, v28, v20
	v_mul_f32_e32 v28, v29, v33
	v_mul_f32_e32 v29, 0xbfb8aa3b, v30
	v_exp_f32_e32 v29, v29
	v_mul_f32_e32 v32, 0xbfb8aa3b, v31
	v_exp_f32_e32 v32, v32
	v_mul_f32_e32 v21, v28, v21
	v_add_f32_e32 v28, 1.0, v29
	v_rcp_f32_e32 v28, v28
	v_add_f32_e32 v29, 1.0, v32
	v_mul_f32_e32 v32, 0xbfb8aa3b, v24
	v_rcp_f32_e32 v29, v29
; #define PG8_STAGE(bufoff, gbase, voff) do { _Pragma("unroll") for (int _i = 0; _i < 2; ++_i) \
;         __builtin_amdgcn_global_load_lds((const unsigned*)((const char*)(gbase) + (voff)[_i]), (PG8_LAS unsigned*)(lds + (bufoff) + ldsw + _i * 8192), 16, 0, 0); } while (0)
; #define PG8_LDA(dst, b, h) do { _Pragma("unroll") for (int m = 0; m < 4; ++m) _Pragma("unroll") for (int k = 0; k < 2; ++k) dst[m][k] = *(const PG8_LAS bf16x8*)(lds + PG8_SA(b, h) + aoff + m * 2048 + k * 1024); } while (0)
; #define PG8_MMA(ai, bj, At, Bt) do { __builtin_amdgcn_s_setprio(1); _Pragma("unroll") for (int m = 0; m < 4; ++m) _Pragma("unroll") for (int n = 0; n < 2; ++n) _Pragma("unroll") for (int k = 0; k < 2; ++k) \
;         acc[ai][bj][m][n] = __builtin_amdgcn_mfma_f32_16x16x32_bf16(Bt[n][k], At[m][k], acc[ai][bj][m][n], 0, 0, 0); __builtin_amdgcn_s_setprio(0); } while (0)
; #define PG8_WAIT_V(n) asm volatile("s_waitcnt vmcnt(" #n ")" ::: "memory")
; #define PG8_WAIT_L(n) asm volatile("s_waitcnt lgkmcnt(" #n ")" ::: "memory")
; #define PG8_BAR __builtin_amdgcn_s_barrier()
; template <class Epi, class Sched, bool ALIGN_EPI = false, bool SP2 = false>
; __device__ __forceinline__ void gemm_phase(PG8_LAS unsigned char* lds, const Gemm g, const Sched& S, const Epi& E) {
;     ...
;             PG8_WAIT_V(8); PG8_WAIT_L(0); PG8_BAR; PG8_MMA(0, 0, At, B0); PG8_MMA(0, 1, At, B1); PG8_BAR; PG8_SCHED;
;             PG8_LDA(At, 0, 1); PG8_STAGE(PG8_SB(0, 0), b2, voffB); PG8_STAGE(PG8_SB(0, 1), b2 + hstep, voffB); PG8_STAGE(PG8_SA(0, 0), a2, voffA);
;             PG8_WAIT_V(8); PG8_WAIT_L(0); PG8_BAR; PG8_MMA(1, 0, At, B0); PG8_MMA(1, 1, At, B1); PG8_BAR; PG8_SCHED;
;     __device__ __forceinline__ void operator()(const f32x4 (&acc)[2][2][4][2], const pg8::Unit& u, int wr, int wc, int fr, int fq) const {
;     ...
;                 const int row = row0 + ai * 128 + m * 16;
;                 const float rs = sumsq ? rsqrtf(sumsq[row] * (1.f / 1024.f) + EPS) : 1.f;
;                 float o[8];
; #pragma unroll
;                 for (int n = 0; n < 2; ++n)
; #pragma unroll
;                     for (int e = 0; e < 4; ++e) { const float g = acc[ai][0][m][n][e] * rs, up = acc[ai][1][m][n][e] * rs; o[4 * n + e] = silu_f(g) * up; }
;                 u32x4 w; w.x = pk2(o[0], o[1]); w.y = pk2(o[2], o[3]); w.z = pk2(o[4], o[5]); w.w = pk2(o[6], o[7]);
;                 *(u32x4*)(H + (size_t)row * DFF + col) = w;
	v_exp_f32_e32 v32, v32
	v_mul_f32_e32 v28, v30, v28
	v_mul_f32_e32 v22, v28, v22
	v_mul_f32_e32 v28, v31, v29
	v_add_f32_e32 v29, 1.0, v32
	v_rcp_f32_e32 v29, v29
	v_mul_f32_e32 v30, 0xbfb8aa3b, v25
	v_exp_f32_e32 v30, v30
	v_mul_f32_e32 v23, v28, v23
	v_mul_f32_e32 v24, v24, v29
	v_mul_f32_e32 v24, v24, v16
	v_add_f32_e32 v16, 1.0, v30
	v_mul_f32_e32 v28, 0xbfb8aa3b, v26
	v_rcp_f32_e32 v16, v16
	v_exp_f32_e32 v28, v28
	v_mul_f32_e32 v29, 0xbfb8aa3b, v27
	v_exp_f32_e32 v29, v29
	v_mul_f32_e32 v16, v25, v16
	v_add_f32_e32 v25, 1.0, v28
	v_rcp_f32_e32 v25, v25
	v_add_f32_e32 v28, 1.0, v29
	v_rcp_f32_e32 v28, v28
	v_mul_f32_e32 v29, v16, v17
	v_mul_f32_e32 v16, v26, v25
	v_mul_f32_e32 v25, v16, v18
	v_mul_f32_e32 v16, v27, v28
	v_mul_f32_e32 v19, v16, v19
	v_cvt_pk_bf16_f32 v16, v20, v21
	v_cvt_pk_bf16_f32 v17, v22, v23
	v_mul_f32_e32 v22, 0xbfb8aa3b, v12
	v_exp_f32_e32 v22, v22
	v_mul_f32_e32 v23, 0xbfb8aa3b, v13
	v_exp_f32_e32 v23, v23
	v_mad_i64_i32 v[20:21], s[100:101], v34, s48, v[112:113]
	v_lshl_add_u64 v[20:21], v[20:21], 0, v[114:115]
	v_cvt_pk_bf16_f32 v18, v24, v29
	v_cvt_pk_bf16_f32 v19, v25, v19
	global_store_dwordx4 v[20:21], v[16:19], off
	s_nop 1
	v_add_f32_e32 v16, 1.0, v22
	v_rcp_f32_e32 v16, v16
	v_add_f32_e32 v17, 1.0, v23
	v_rcp_f32_e32 v17, v17
	v_add_u32_e32 v18, 0xb0, v228
	v_mul_f32_e32 v12, v12, v16
	v_mul_f32_e32 v4, v12, v4
	v_mul_f32_e32 v12, v13, v17
	v_mul_f32_e32 v13, 0xbfb8aa3b, v14
	v_exp_f32_e32 v13, v13
	v_mul_f32_e32 v16, 0xbfb8aa3b, v15
	v_exp_f32_e32 v16, v16
	v_mul_f32_e32 v5, v12, v5
	v_add_f32_e32 v12, 1.0, v13
	v_rcp_f32_e32 v12, v12
	v_add_f32_e32 v13, 1.0, v16
	v_mul_f32_e32 v16, 0xbfb8aa3b, v8
	v_rcp_f32_e32 v13, v13
	v_exp_f32_e32 v16, v16
	v_mul_f32_e32 v12, v14, v12
	v_mul_f32_e32 v6, v12, v6
	v_mul_f32_e32 v12, v15, v13
	v_add_f32_e32 v13, 1.0, v16
	v_rcp_f32_e32 v13, v13
	v_mul_f32_e32 v14, 0xbfb8aa3b, v9
	v_exp_f32_e32 v14, v14
	v_mul_f32_e32 v7, v12, v7
	v_mul_f32_e32 v8, v8, v13
	v_mul_f32_e32 v8, v8, v0
	v_add_f32_e32 v0, 1.0, v14
	v_mul_f32_e32 v12, 0xbfb8aa3b, v10
	v_rcp_f32_e32 v0, v0
	v_exp_f32_e32 v12, v12
	v_mul_f32_e32 v13, 0xbfb8aa3b, v11
	v_exp_f32_e32 v13, v13
	v_mul_f32_e32 v0, v9, v0
	v_add_f32_e32 v9, 1.0, v12
	v_rcp_f32_e32 v9, v9
	v_add_f32_e32 v12, 1.0, v13
	v_rcp_f32_e32 v12, v12
	v_mul_f32_e32 v13, v0, v1
	v_mul_f32_e32 v0, v10, v9
	v_mul_f32_e32 v9, v0, v2
	v_mul_f32_e32 v0, v11, v12
	v_mul_f32_e32 v3, v0, v3
	v_cvt_pk_bf16_f32 v0, v4, v5
	v_mad_i64_i32 v[4:5], s[100:101], v18, s48, v[112:113]
	v_lshl_add_u64 v[4:5], v[4:5], 0, v[114:115]
	v_cvt_pk_bf16_f32 v1, v6, v7
	v_cvt_pk_bf16_f32 v2, v8, v13
	v_cvt_pk_bf16_f32 v3, v9, v3
	global_store_dwordx4 v[4:5], v[0:3], off
	s_waitcnt vmcnt(16)
	s_waitcnt lgkmcnt(0)
	s_barrier
	s_setprio 1
	v_mfma_f32_16x16x32_bf16 v[124:127], v[150:153], v[182:185], 0
	v_mfma_f32_16x16x32_bf16 v[120:123], v[158:161], v[182:185], 0
	v_mfma_f32_16x16x32_bf16 v[108:111], v[150:153], v[196:199], 0
	v_mfma_f32_16x16x32_bf16 v[104:107], v[158:161], v[196:199], 0
	v_mfma_f32_16x16x32_bf16 v[92:95], v[150:153], v[204:207], 0
	v_mfma_f32_16x16x32_bf16 v[88:91], v[158:161], v[204:207], 0
	v_mfma_f32_16x16x32_bf16 v[76:79], v[150:153], v[212:215], 0
	v_mfma_f32_16x16x32_bf16 v[72:75], v[158:161], v[212:215], 0
	v_mfma_f32_16x16x32_bf16 v[124:127], v[154:157], v[192:195], v[124:127]
	v_mfma_f32_16x16x32_bf16 v[120:123], v[162:165], v[192:195], v[120:123]
	v_mfma_f32_16x16x32_bf16 v[108:111], v[154:157], v[200:203], v[108:111]
	v_mfma_f32_16x16x32_bf16 v[104:107], v[162:165], v[200:203], v[104:107]
	v_mfma_f32_16x16x32_bf16 v[92:95], v[154:157], v[208:211], v[92:95]
	v_mfma_f32_16x16x32_bf16 v[88:91], v[162:165], v[208:211], v[88:91]
	v_mfma_f32_16x16x32_bf16 v[76:79], v[154:157], v[216:219], v[76:79]
	v_mfma_f32_16x16x32_bf16 v[72:75], v[162:165], v[216:219], v[72:75]
	v_mfma_f32_16x16x32_bf16 v[116:119], v[166:169], v[182:185], 0
	v_mfma_f32_16x16x32_bf16 v[112:115], v[174:177], v[182:185], 0
	v_mfma_f32_16x16x32_bf16 v[100:103], v[166:169], v[196:199], 0
	v_mfma_f32_16x16x32_bf16 v[96:99], v[174:177], v[196:199], 0
	v_mfma_f32_16x16x32_bf16 v[84:87], v[166:169], v[204:207], 0
	v_mfma_f32_16x16x32_bf16 v[80:83], v[174:177], v[204:207], 0
	v_mfma_f32_16x16x32_bf16 v[68:71], v[166:169], v[212:215], 0
	v_mfma_f32_16x16x32_bf16 v[64:67], v[174:177], v[212:215], 0
	v_mfma_f32_16x16x32_bf16 v[116:119], v[170:173], v[192:195], v[116:119]
	v_mfma_f32_16x16x32_bf16 v[112:115], v[178:181], v[192:195], v[112:115]
	v_mfma_f32_16x16x32_bf16 v[100:103], v[170:173], v[200:203], v[100:103]
	v_mfma_f32_16x16x32_bf16 v[96:99], v[178:181], v[200:203], v[96:99]
	v_mfma_f32_16x16x32_bf16 v[84:87], v[170:173], v[208:211], v[84:87]
	v_mfma_f32_16x16x32_bf16 v[80:83], v[178:181], v[208:211], v[80:83]
	v_mfma_f32_16x16x32_bf16 v[68:71], v[170:173], v[216:219], v[68:71]
	v_mfma_f32_16x16x32_bf16 v[64:67], v[178:181], v[216:219], v[64:67]
	s_setprio 0
	s_barrier
	s_add_i32 s55, s46, s35
	v_lshl_add_u64 v[186:187], s[24:25], 0, v[132:133]
	s_mov_b32 m0, s55
	ds_read_b128 v[182:185], v149 offset:16384
	ds_read_b128 v[192:195], v149 offset:17408
	ds_read_b128 v[196:199], v149 offset:18432
	ds_read_b128 v[200:203], v149 offset:19456
	ds_read_b128 v[204:207], v149 offset:20480
	ds_read_b128 v[208:211], v149 offset:21504
	ds_read_b128 v[212:215], v149 offset:22528
	ds_read_b128 v[216:219], v149 offset:23552
	global_load_lds_dwordx4 v[186:187], off
	s_add_i32 m0, s55, 0x2000
	s_add_u32 s56, s24, 0x40000
	v_lshl_add_u64 v[220:221], s[24:25], 0, v[128:129]
	s_addc_u32 s57, s25, 0
	s_add_i32 s55, s47, s35
	global_load_lds_dwordx4 v[220:221], off
	v_lshl_add_u64 v[222:223], s[56:57], 0, v[132:133]
	s_mov_b32 m0, s55
	v_lshl_add_u64 v[224:225], s[30:31], 0, v[130:131]
	global_load_lds_dwordx4 v[222:223], off
	v_lshl_add_u64 v[222:223], s[56:57], 0, v[128:129]
	s_add_i32 m0, s55, 0x2000
	s_nop 0
	global_load_lds_dwordx4 v[222:223], off
	v_lshl_add_u64 v[222:223], s[30:31], 0, v[134:135]
	s_mov_b32 m0, s21
	s_nop 0
	global_load_lds_dwordx4 v[222:223], off
	s_mov_b32 m0, s38
	s_nop 0
	global_load_lds_dwordx4 v[224:225], off
	s_waitcnt vmcnt(16)
	s_waitcnt lgkmcnt(0)
	s_barrier
; #define PG8_STAGE(bufoff, gbase, voff) do { _Pragma("unroll") for (int _i = 0; _i < 2; ++_i) \
;         __builtin_amdgcn_global_load_lds((const unsigned*)((const char*)(gbase) + (voff)[_i]), (PG8_LAS unsigned*)(lds + (bufoff) + ldsw + _i * 8192), 16, 0, 0); } while (0)
; #define PG8_LDA(dst, b, h) do { _Pragma("unroll") for (int m = 0; m < 4; ++m) _Pragma("unroll") for (int k = 0; k < 2; ++k) dst[m][k] = *(const PG8_LAS bf16x8*)(lds + PG8_SA(b, h) + aoff + m * 2048 + k * 1024); } while (0)
; #define PG8_LDB(dst, b, h) do { _Pragma("unroll") for (int n = 0; n < 2; ++n) _Pragma("unroll") for (int k = 0; k < 2; ++k) dst[n][k] = *(const PG8_LAS bf16x8*)(lds + PG8_SB(b, h) + boff + n * 2048 + k * 1024); } while (0)
; #define PG8_MMA(ai, bj, At, Bt) do { __builtin_amdgcn_s_setprio(1); _Pragma("unroll") for (int m = 0; m < 4; ++m) _Pragma("unroll") for (int n = 0; n < 2; ++n) _Pragma("unroll") for (int k = 0; k < 2; ++k) \
;         acc[ai][bj][m][n] = __builtin_amdgcn_mfma_f32_16x16x32_bf16(Bt[n][k], At[m][k], acc[ai][bj][m][n], 0, 0, 0); __builtin_amdgcn_s_setprio(0); } while (0)
; #define PG8_WAIT_V(n) asm volatile("s_waitcnt vmcnt(" #n ")" ::: "memory")
; #define PG8_WAIT_L(n) asm volatile("s_waitcnt lgkmcnt(" #n ")" ::: "memory")
; #define PG8_BAR __builtin_amdgcn_s_barrier()
; #define PG8_SCHED __builtin_amdgcn_sched_barrier(0)
; template <class Epi, class Sched, bool ALIGN_EPI = false, bool SP2 = false>
; __device__ __forceinline__ void gemm_phase(PG8_LAS unsigned char* lds, const Gemm g, const Sched& S, const Epi& E) {
;     ...
;             PG8_WAIT_V(8); PG8_WAIT_L(0); PG8_BAR; PG8_MMA(1, 0, At, B0); PG8_MMA(1, 1, At, B1); PG8_BAR; PG8_SCHED;
;             PG8_LDB(B0, 1, 0); PG8_LDB(B1, 1, 1); PG8_SCHED; PG8_LDA(At, 1, 0); PG8_STAGE(PG8_SA(0, 1), a2 + hstep, voffA);
;             PG8_WAIT_V(8); PG8_WAIT_L(0); PG8_BAR; PG8_MMA(0, 0, At, B0); PG8_MMA(0, 1, At, B1); PG8_BAR; PG8_SCHED;
	s_setprio 1
	v_mfma_f32_16x16x32_bf16 v[60:63], v[150:153], v[182:185], 0
	v_mfma_f32_16x16x32_bf16 v[56:59], v[158:161], v[182:185], 0
	v_mfma_f32_16x16x32_bf16 v[44:47], v[150:153], v[196:199], 0
	v_mfma_f32_16x16x32_bf16 v[40:43], v[158:161], v[196:199], 0
	v_mfma_f32_16x16x32_bf16 v[28:31], v[150:153], v[204:207], 0
	v_mfma_f32_16x16x32_bf16 v[24:27], v[158:161], v[204:207], 0
	v_mfma_f32_16x16x32_bf16 v[12:15], v[150:153], v[212:215], 0
	v_mfma_f32_16x16x32_bf16 v[8:11], v[158:161], v[212:215], 0
	v_mfma_f32_16x16x32_bf16 v[60:63], v[154:157], v[192:195], v[60:63]
	v_mfma_f32_16x16x32_bf16 v[56:59], v[162:165], v[192:195], v[56:59]
	v_mfma_f32_16x16x32_bf16 v[44:47], v[154:157], v[200:203], v[44:47]
	v_mfma_f32_16x16x32_bf16 v[40:43], v[162:165], v[200:203], v[40:43]
	v_mfma_f32_16x16x32_bf16 v[28:31], v[154:157], v[208:211], v[28:31]
	v_mfma_f32_16x16x32_bf16 v[24:27], v[162:165], v[208:211], v[24:27]
	v_mfma_f32_16x16x32_bf16 v[12:15], v[154:157], v[216:219], v[12:15]
	v_mfma_f32_16x16x32_bf16 v[8:11], v[162:165], v[216:219], v[8:11]
	v_mfma_f32_16x16x32_bf16 v[52:55], v[166:169], v[182:185], 0
	v_mfma_f32_16x16x32_bf16 v[48:51], v[174:177], v[182:185], 0
	v_mfma_f32_16x16x32_bf16 v[36:39], v[166:169], v[196:199], 0
	v_mfma_f32_16x16x32_bf16 v[32:35], v[174:177], v[196:199], 0
	v_mfma_f32_16x16x32_bf16 v[20:23], v[166:169], v[204:207], 0
	v_mfma_f32_16x16x32_bf16 v[16:19], v[174:177], v[204:207], 0
	v_mfma_f32_16x16x32_bf16 v[4:7], v[166:169], v[212:215], 0
	v_mfma_f32_16x16x32_bf16 v[0:3], v[174:177], v[212:215], 0
	v_mfma_f32_16x16x32_bf16 v[52:55], v[170:173], v[192:195], v[52:55]
	v_mfma_f32_16x16x32_bf16 v[48:51], v[178:181], v[192:195], v[48:51]
	v_mfma_f32_16x16x32_bf16 v[36:39], v[170:173], v[200:203], v[36:39]
	v_mfma_f32_16x16x32_bf16 v[32:35], v[178:181], v[200:203], v[32:35]
	v_mfma_f32_16x16x32_bf16 v[20:23], v[170:173], v[208:211], v[20:23]
	v_mfma_f32_16x16x32_bf16 v[16:19], v[178:181], v[208:211], v[16:19]
	v_mfma_f32_16x16x32_bf16 v[4:7], v[170:173], v[216:219], v[4:7]
	v_mfma_f32_16x16x32_bf16 v[0:3], v[178:181], v[216:219], v[0:3]
	s_setprio 0
	s_barrier
	s_add_i32 s55, 0, 0x18000
	s_add_i32 s56, 0, 0x1c000
	v_add_u32_e32 v162, s55, v145
	v_add_u32_e32 v178, s56, v145
	ds_read_b128 v[150:153], v162
	ds_read_b128 v[154:157], v162 offset:1024
	ds_read_b128 v[158:161], v162 offset:2048
	ds_read_b128 v[162:165], v162 offset:3072
	ds_read_b128 v[166:169], v178
	ds_read_b128 v[170:173], v178 offset:1024
	ds_read_b128 v[174:177], v178 offset:2048
	ds_read_b128 v[178:181], v178 offset:3072
	s_add_u32 s30, s30, 0x40000
	s_addc_u32 s31, s31, 0
	s_mov_b32 m0, s39
	v_lshl_add_u64 v[226:227], s[30:31], 0, v[134:135]
	ds_read_b128 v[182:185], v149 offset:32768
	ds_read_b128 v[192:195], v149 offset:33792
	ds_read_b128 v[196:199], v149 offset:34816
	ds_read_b128 v[200:203], v149 offset:35840
	ds_read_b128 v[204:207], v149 offset:36864
	ds_read_b128 v[208:211], v149 offset:37888
	ds_read_b128 v[212:215], v149 offset:38912
	ds_read_b128 v[216:219], v149 offset:39936
	global_load_lds_dwordx4 v[226:227], off
	v_lshl_add_u64 v[226:227], s[30:31], 0, v[130:131]
	s_mov_b32 m0, s40
	s_nop 0
	global_load_lds_dwordx4 v[226:227], off
	s_waitcnt vmcnt(12)
	s_waitcnt lgkmcnt(0)
	s_barrier
	s_setprio 1
	v_mfma_f32_16x16x32_bf16 v[124:127], v[150:153], v[182:185], v[124:127]
	v_mfma_f32_16x16x32_bf16 v[120:123], v[158:161], v[182:185], v[120:123]
	v_mfma_f32_16x16x32_bf16 v[108:111], v[150:153], v[196:199], v[108:111]
	v_mfma_f32_16x16x32_bf16 v[104:107], v[158:161], v[196:199], v[104:107]
	v_mfma_f32_16x16x32_bf16 v[92:95], v[150:153], v[204:207], v[92:95]
	v_mfma_f32_16x16x32_bf16 v[88:91], v[158:161], v[204:207], v[88:91]
	v_mfma_f32_16x16x32_bf16 v[76:79], v[150:153], v[212:215], v[76:79]
	v_mfma_f32_16x16x32_bf16 v[72:75], v[158:161], v[212:215], v[72:75]
	v_mfma_f32_16x16x32_bf16 v[124:127], v[154:157], v[192:195], v[124:127]
	v_mfma_f32_16x16x32_bf16 v[120:123], v[162:165], v[192:195], v[120:123]
	v_mfma_f32_16x16x32_bf16 v[108:111], v[154:157], v[200:203], v[108:111]
	v_mfma_f32_16x16x32_bf16 v[104:107], v[162:165], v[200:203], v[104:107]
	v_mfma_f32_16x16x32_bf16 v[92:95], v[154:157], v[208:211], v[92:95]
	v_mfma_f32_16x16x32_bf16 v[88:91], v[162:165], v[208:211], v[88:91]
	v_mfma_f32_16x16x32_bf16 v[76:79], v[154:157], v[216:219], v[76:79]
	v_mfma_f32_16x16x32_bf16 v[72:75], v[162:165], v[216:219], v[72:75]
	v_mfma_f32_16x16x32_bf16 v[116:119], v[166:169], v[182:185], v[116:119]
	v_mfma_f32_16x16x32_bf16 v[112:115], v[174:177], v[182:185], v[112:115]
	v_mfma_f32_16x16x32_bf16 v[100:103], v[166:169], v[196:199], v[100:103]
	v_mfma_f32_16x16x32_bf16 v[96:99], v[174:177], v[196:199], v[96:99]
	v_mfma_f32_16x16x32_bf16 v[84:87], v[166:169], v[204:207], v[84:87]
	v_mfma_f32_16x16x32_bf16 v[80:83], v[174:177], v[204:207], v[80:83]
	v_mfma_f32_16x16x32_bf16 v[68:71], v[166:169], v[212:215], v[68:71]
	v_mfma_f32_16x16x32_bf16 v[64:67], v[174:177], v[212:215], v[64:67]
	v_mfma_f32_16x16x32_bf16 v[116:119], v[170:173], v[192:195], v[116:119]
	v_mfma_f32_16x16x32_bf16 v[112:115], v[178:181], v[192:195], v[112:115]
	v_mfma_f32_16x16x32_bf16 v[100:103], v[170:173], v[200:203], v[100:103]
	v_mfma_f32_16x16x32_bf16 v[96:99], v[178:181], v[200:203], v[96:99]
	v_mfma_f32_16x16x32_bf16 v[84:87], v[170:173], v[208:211], v[84:87]
	v_mfma_f32_16x16x32_bf16 v[80:83], v[178:181], v[208:211], v[80:83]
	v_mfma_f32_16x16x32_bf16 v[68:71], v[170:173], v[216:219], v[68:71]
	v_mfma_f32_16x16x32_bf16 v[64:67], v[178:181], v[216:219], v[64:67]
	s_setprio 0
	s_barrier
; #define PG8_STAGE(bufoff, gbase, voff) do { _Pragma("unroll") for (int _i = 0; _i < 2; ++_i) \
;         __builtin_amdgcn_global_load_lds((const unsigned*)((const char*)(gbase) + (voff)[_i]), (PG8_LAS unsigned*)(lds + (bufoff) + ldsw + _i * 8192), 16, 0, 0); } while (0)
; #define PG8_LDA(dst, b, h) do { _Pragma("unroll") for (int m = 0; m < 4; ++m) _Pragma("unroll") for (int k = 0; k < 2; ++k) dst[m][k] = *(const PG8_LAS bf16x8*)(lds + PG8_SA(b, h) + aoff + m * 2048 + k * 1024); } while (0)
; #define PG8_MMA(ai, bj, At, Bt) do { __builtin_amdgcn_s_setprio(1); _Pragma("unroll") for (int m = 0; m < 4; ++m) _Pragma("unroll") for (int n = 0; n < 2; ++n) _Pragma("unroll") for (int k = 0; k < 2; ++k) \
;         acc[ai][bj][m][n] = __builtin_amdgcn_mfma_f32_16x16x32_bf16(Bt[n][k], At[m][k], acc[ai][bj][m][n], 0, 0, 0); __builtin_amdgcn_s_setprio(0); } while (0)
; #define PG8_WAIT_V(n) asm volatile("s_waitcnt vmcnt(" #n ")" ::: "memory")
; #define PG8_WAIT_L(n) asm volatile("s_waitcnt lgkmcnt(" #n ")" ::: "memory")
; #define PG8_BAR __builtin_amdgcn_s_barrier()
; #define PG8_SCHED __builtin_amdgcn_sched_barrier(0)
; template <class Epi, class Sched, bool ALIGN_EPI = false, bool SP2 = false>
; __device__ __forceinline__ void gemm_phase(PG8_LAS unsigned char* lds, const Gemm g, const Sched& S, const Epi& E) {
;     ...
;             PG8_LDA(At, 1, 1); PG8_STAGE(PG8_SB(1, 0), b3, voffB); PG8_STAGE(PG8_SB(1, 1), b3 + hstep, voffB); PG8_STAGE(PG8_SA(1, 0), a3, voffA);
;             PG8_WAIT_V(8); PG8_WAIT_L(0); PG8_BAR; PG8_MMA(1, 0, At, B0); PG8_MMA(1, 1, At, B1); PG8_BAR; PG8_SCHED;
	s_add_i32 s30, s55, s35
	v_lshl_add_u64 v[186:187], v[186:187], 0, s[4:5]
	s_mov_b32 m0, s30
	ds_read_b128 v[182:185], v149 offset:49152
	ds_read_b128 v[192:195], v149 offset:50176
	ds_read_b128 v[196:199], v149 offset:51200
	ds_read_b128 v[200:203], v149 offset:52224
	ds_read_b128 v[204:207], v149 offset:53248
	ds_read_b128 v[208:211], v149 offset:54272
	ds_read_b128 v[212:215], v149 offset:55296
	ds_read_b128 v[216:219], v149 offset:56320
	global_load_lds_dwordx4 v[186:187], off
	s_add_i32 m0, s30, 0x2000
	s_add_u32 s24, s24, 0x40080
	v_lshl_add_u64 v[186:187], v[220:221], 0, s[4:5]
	s_addc_u32 s25, s25, 0
	s_add_i32 s30, s56, s35
	global_load_lds_dwordx4 v[186:187], off
	v_lshl_add_u64 v[186:187], s[24:25], 0, v[132:133]
	s_mov_b32 m0, s30
	s_nop 0
	global_load_lds_dwordx4 v[186:187], off
	v_lshl_add_u64 v[186:187], s[24:25], 0, v[128:129]
	s_add_i32 m0, s30, 0x2000
	s_nop 0
	global_load_lds_dwordx4 v[186:187], off
	v_lshl_add_u64 v[186:187], v[222:223], 0, s[4:5]
	s_mov_b32 m0, s42
	s_nop 0
	global_load_lds_dwordx4 v[186:187], off
	v_lshl_add_u64 v[186:187], v[224:225], 0, s[4:5]
	s_mov_b32 m0, s43
	s_nop 0
	global_load_lds_dwordx4 v[186:187], off
	s_waitcnt vmcnt(8)
	s_waitcnt lgkmcnt(0)
	s_barrier
	s_setprio 1
	v_mfma_f32_16x16x32_bf16 v[60:63], v[150:153], v[182:185], v[60:63]
	v_mfma_f32_16x16x32_bf16 v[56:59], v[158:161], v[182:185], v[56:59]
	v_mfma_f32_16x16x32_bf16 v[44:47], v[150:153], v[196:199], v[44:47]
	v_mfma_f32_16x16x32_bf16 v[40:43], v[158:161], v[196:199], v[40:43]
	v_mfma_f32_16x16x32_bf16 v[28:31], v[150:153], v[204:207], v[28:31]
	v_mfma_f32_16x16x32_bf16 v[24:27], v[158:161], v[204:207], v[24:27]
	v_mfma_f32_16x16x32_bf16 v[12:15], v[150:153], v[212:215], v[12:15]
	v_mfma_f32_16x16x32_bf16 v[8:11], v[158:161], v[212:215], v[8:11]
	v_mfma_f32_16x16x32_bf16 v[60:63], v[154:157], v[192:195], v[60:63]
	v_mfma_f32_16x16x32_bf16 v[56:59], v[162:165], v[192:195], v[56:59]
	v_mfma_f32_16x16x32_bf16 v[44:47], v[154:157], v[200:203], v[44:47]
	v_mfma_f32_16x16x32_bf16 v[40:43], v[162:165], v[200:203], v[40:43]
	v_mfma_f32_16x16x32_bf16 v[28:31], v[154:157], v[208:211], v[28:31]
	v_mfma_f32_16x16x32_bf16 v[24:27], v[162:165], v[208:211], v[24:27]
	v_mfma_f32_16x16x32_bf16 v[12:15], v[154:157], v[216:219], v[12:15]
	v_mfma_f32_16x16x32_bf16 v[8:11], v[162:165], v[216:219], v[8:11]
	v_mfma_f32_16x16x32_bf16 v[52:55], v[166:169], v[182:185], v[52:55]
	v_mfma_f32_16x16x32_bf16 v[48:51], v[174:177], v[182:185], v[48:51]
	v_mfma_f32_16x16x32_bf16 v[36:39], v[166:169], v[196:199], v[36:39]
	v_mfma_f32_16x16x32_bf16 v[32:35], v[174:177], v[196:199], v[32:35]
	v_mfma_f32_16x16x32_bf16 v[20:23], v[166:169], v[204:207], v[20:23]
	v_mfma_f32_16x16x32_bf16 v[16:19], v[174:177], v[204:207], v[16:19]
	v_mfma_f32_16x16x32_bf16 v[4:7], v[166:169], v[212:215], v[4:7]
	v_mfma_f32_16x16x32_bf16 v[0:3], v[174:177], v[212:215], v[0:3]
	v_mfma_f32_16x16x32_bf16 v[52:55], v[170:173], v[192:195], v[52:55]
	v_mfma_f32_16x16x32_bf16 v[48:51], v[178:181], v[192:195], v[48:51]
	v_mfma_f32_16x16x32_bf16 v[36:39], v[170:173], v[200:203], v[36:39]
	v_mfma_f32_16x16x32_bf16 v[32:35], v[178:181], v[200:203], v[32:35]
	v_mfma_f32_16x16x32_bf16 v[20:23], v[170:173], v[208:211], v[20:23]
	v_mfma_f32_16x16x32_bf16 v[16:19], v[178:181], v[208:211], v[16:19]
	v_mfma_f32_16x16x32_bf16 v[4:7], v[170:173], v[216:219], v[4:7]
	v_mfma_f32_16x16x32_bf16 v[0:3], v[178:181], v[216:219], v[0:3]
	s_setprio 0
	s_barrier
	s_add_i32 s54, s54, 2
	s_add_u32 s22, s22, 0x100
	s_addc_u32 s23, s23, 0
	s_add_u32 s52, s52, 0x100
	s_addc_u32 s53, s53, 0
	s_branch .LBB0_192
